# v30 + SSD chunk scan via DPP row_shr/row_bcast instead of 6 ds_bpermute round trips
# baseline (speedup 1.0000x reference)
.LBB0_262:
	s_or_b64 exec, exec, s[84:85]
	s_and_saveexec_b64 s[84:85], s[6:7]
	s_cbranch_execz .LBB0_264
	s_waitcnt vmcnt(8)
	v_mul_f32_e64 v0, v53, -v57
	s_nop 4
	v_add_f32_dpp v0, v0, v0 row_shr:1 row_mask:0xf bank_mask:0xf bound_ctrl:0
	s_nop 1
	v_add_f32_dpp v0, v0, v0 row_shr:2 row_mask:0xf bank_mask:0xf bound_ctrl:0
	s_nop 1
	v_add_f32_dpp v0, v0, v0 row_shr:4 row_mask:0xf bank_mask:0xf bound_ctrl:0
	s_nop 1
	v_add_f32_dpp v0, v0, v0 row_shr:8 row_mask:0xf bank_mask:0xf bound_ctrl:0
	s_nop 1
	v_add_f32_dpp v0, v0, v0 row_bcast:15 row_mask:0xa bank_mask:0xf
	s_nop 1
	v_add_f32_dpp v0, v0, v0 row_bcast:31 row_mask:0xc bank_mask:0xf
	s_nop 1
	ds_write_b32 v61, v0
	ds_write_b32 v67, v53
